# E28: grid barrier flat release: waiting workgroups poll TOPGEN instead of their XCD's XGEN, leaders' XGEN increments removed; on E23
# speedup vs baseline: 1.0078x; 1.0078x over previous
.LBB0_16:
	v_readlane_b32 s6, v252, 0
	v_readlane_b32 s7, v252, 1
	s_load_dwordx2 s[4:5], s[6:7], 0x48
	s_andn2_b64 vcc, exec, s[0:1]
	v_mbcnt_lo_u32_b32 v63, -1, 0
	s_waitcnt lgkmcnt(0)
	v_writelane_b32 v252, s4, 12
	s_nop 1
	v_writelane_b32 v252, s5, 13
	s_load_dwordx2 s[4:5], s[6:7], 0x58
	s_waitcnt lgkmcnt(0)
	v_writelane_b32 v252, s4, 14
	s_nop 1
	v_writelane_b32 v252, s5, 15
	v_writelane_b32 v252, s90, 16
	s_nop 1
	v_writelane_b32 v252, s91, 17
	v_writelane_b32 v252, s97, 18
	v_writelane_b32 v252, s12, 19
	s_cbranch_vccnz .LBB0_274
	v_mov_b32_e32 v3, v0
	s_mov_b32 s15, 0x7f800000
	v_readfirstlane_b32 s0, v3
	s_ashr_i32 s9, s0, 6
	s_lshl_b32 s0, s9, 14
	s_add_i32 s17, s0, 0
	s_add_u32 s0, s90, 0x4200
	s_addc_u32 s1, s91, 0
	s_add_u32 s52, s90, 0x4400
	s_addc_u32 s53, s91, 0
	s_add_u32 s54, s90, 0x4500
	s_addc_u32 s55, s91, 0
	s_add_u32 s56, s90, 0x4600
	s_addc_u32 s57, s91, 0
	s_add_u32 s58, s90, 0x4700
	s_addc_u32 s59, s91, 0
	s_add_u32 s60, s90, 0x4800
	s_addc_u32 s61, s91, 0
	s_add_u32 s62, s90, 0x4900
	s_addc_u32 s63, s91, 0
	s_add_u32 s64, s90, 0x4a00
	s_addc_u32 s65, s91, 0
	s_add_u32 s68, s90, 0x4b00
	s_addc_u32 s69, s91, 0
	s_add_u32 s70, s90, 0x4c00
	s_addc_u32 s71, s91, 0
	s_add_u32 s74, s90, 0x4d00
	s_addc_u32 s75, s91, 0
	s_add_u32 s78, s90, 0x4e00
	s_addc_u32 s79, s91, 0
	s_add_u32 s80, s90, 0x4f00
	s_addc_u32 s81, s91, 0
	s_add_u32 s82, s90, 0x5000
	s_addc_u32 s83, s91, 0
	s_add_u32 s84, s90, 0x5100
	s_addc_u32 s85, s91, 0
	s_add_u32 s86, s90, 0x5200
	s_addc_u32 s87, s91, 0
	s_add_u32 s88, s90, 0x5300
	s_addc_u32 s89, s91, 0
	s_cmp_eq_u32 s13, 15
	s_cselect_b64 s[4:5], -1, 0
	v_writelane_b32 v252, s4, 20
	s_cmp_eq_u32 s13, 14
	v_and_b32_e32 v62, 63, v3
	v_writelane_b32 v252, s5, 21
	s_cselect_b64 s[4:5], -1, 0
	v_writelane_b32 v252, s4, 22
	s_cmp_eq_u32 s13, 13
	v_cvt_f32_ubyte0_e32 v1, v62
	v_writelane_b32 v252, s5, 23
	s_cselect_b64 s[4:5], -1, 0
	v_writelane_b32 v252, s4, 24
	s_cmp_eq_u32 s13, 12
	v_mul_f32_e32 v2, 0x3d000000, v1
	v_writelane_b32 v252, s5, 25
	s_cselect_b64 s[4:5], -1, 0
	v_writelane_b32 v252, s4, 26
	s_cmp_eq_u32 s13, 11
	v_mul_f32_e32 v1, 0.5, v2
	v_writelane_b32 v252, s5, 27
	s_cselect_b64 s[4:5], -1, 0
	v_writelane_b32 v252, s4, 28
	s_cmp_eq_u32 s13, 10
	v_fract_f32_e32 v4, v1
	v_writelane_b32 v252, s5, 29
	s_cselect_b64 s[4:5], -1, 0
	v_writelane_b32 v252, s4, 30
	s_cmp_eq_u32 s13, 9
	v_add_f32_e32 v4, v4, v4
	v_writelane_b32 v252, s5, 31
	s_cselect_b64 s[4:5], -1, 0
	v_writelane_b32 v252, s4, 32
	s_cmp_eq_u32 s13, 8
	v_cmp_neq_f32_e32 vcc, s15, v1
	v_writelane_b32 v252, s5, 33
	s_cselect_b64 s[4:5], -1, 0
	v_writelane_b32 v252, s4, 34
	s_cmp_eq_u32 s13, 7
	v_cndmask_b32_e32 v1, 0, v4, vcc
	v_writelane_b32 v252, s5, 35
	s_cselect_b64 s[4:5], -1, 0
	v_writelane_b32 v252, s4, 36
	s_cmp_eq_u32 s13, 6
	v_cmp_lt_f32_e32 vcc, 1.0, v2
	v_writelane_b32 v252, s5, 37
	s_cselect_b64 s[4:5], -1, 0
	v_writelane_b32 v252, s4, 38
	s_cmp_eq_u32 s13, 5
	v_cndmask_b32_e32 v4, v2, v1, vcc
	v_writelane_b32 v252, s5, 39
	s_cselect_b64 s[4:5], -1, 0
	v_writelane_b32 v252, s4, 40
	s_cmp_eq_u32 s13, 4
	s_mov_b64 s[6:7], s[90:91]
	v_writelane_b32 v252, s5, 41
	s_cselect_b64 s[4:5], -1, 0
	v_writelane_b32 v252, s4, 42
	s_cmp_eq_u32 s13, 3
	v_add_f32_e32 v1, v4, v4
	v_writelane_b32 v252, s5, 43
	s_cselect_b64 s[4:5], -1, 0
	v_writelane_b32 v252, s4, 44
	s_cmp_eq_u32 s13, 2
	v_rndne_f32_e32 v1, v1
	v_writelane_b32 v252, s5, 45
	s_cselect_b64 s[4:5], -1, 0
	v_writelane_b32 v252, s4, 46
	s_cmp_eq_u32 s13, 1
	v_fmac_f32_e32 v4, -0.5, v1
	v_writelane_b32 v252, s5, 47
	s_cselect_b64 s[4:5], -1, 0
	v_writelane_b32 v252, s4, 48
	s_cmp_eq_u32 s13, 0
	v_cvt_i32_f32_e32 v5, v1
	v_writelane_b32 v252, s5, 49
	s_cselect_b64 s[4:5], -1, 0
	s_lshl_b32 s2, s13, 8
	s_lshl_b32 s90, s13, 6
	v_writelane_b32 v252, s4, 50
	s_add_u32 s2, s48, s2
	v_mul_f32_e32 v7, v4, v4
	v_writelane_b32 v252, s5, 51
	s_addc_u32 s4, s49, 0
	s_add_u32 s10, s2, 0x1400
	v_mov_b32_e32 v1, 0xbf1f24be
	s_addc_u32 s11, s4, 0
	v_fmamk_f32 v8, v7, 0x3e75aa41, v1
	v_writelane_b32 v252, s10, 52
	v_fmaak_f32 v8, v7, v8, 0x40234736
	v_fmaak_f32 v8, v7, v8, 0xc0a55e0e
	v_writelane_b32 v252, s11, 53
	s_add_u32 s10, s6, 0x7400
	v_mul_f32_e32 v9, v4, v7
	s_addc_u32 s11, s7, 0
	v_mul_f32_e32 v8, v9, v8
	v_mov_b32_e32 v65, 0x3e642e9d
	s_add_u32 s96, s6, 0x7500
	v_fmac_f32_e32 v8, 0x40490fdb, v4
	v_fmamk_f32 v4, v7, 0x3d4be544, v65
	v_writelane_b32 v252, s10, 54
	s_addc_u32 s97, s7, 0
	v_fmaak_f32 v4, v7, v4, 0xbfaad1da
	v_writelane_b32 v252, s11, 55
	s_add_u32 s66, s6, 0x7500
	v_fmaak_f32 v4, v7, v4, 0x4081e0d3
	s_addc_u32 s67, s7, 0
	v_readlane_b32 s40, v252, 0
	s_lshl_b32 s2, s9, 2
	v_and_b32_e32 v6, 2, v5
	v_fmaak_f32 v4, v7, v4, 0xc09de9e6
	v_and_b32_e32 v5, 1, v5
	v_readlane_b32 s41, v252, 1
	v_writelane_b32 v252, s2, 56
	v_cmp_gt_u32_e64 s[4:5], 33, v62
	v_fma_f32 v4, v7, v4, 1.0
	v_cmp_eq_u32_e32 vcc, 0, v5
	v_writelane_b32 v252, s4, 58
	s_mov_b32 s91, 0
	v_cndmask_b32_e64 v4, -v8, v4, vcc
	v_cmp_eq_u32_e32 vcc, 0, v6
	v_writelane_b32 v252, s5, 59
	v_mov_b32_e32 v69, 0x7fc00000
	v_cndmask_b32_e64 v4, -v4, v4, vcc
	v_cmp_lg_f32_e32 vcc, s15, v2
	v_writelane_b32 v252, s90, 60
	v_xor_b32_e32 v2, 32, v3
	v_cndmask_b32_e32 v71, v69, v4, vcc
	v_cmp_lt_u32_e32 vcc, 32, v62
	s_waitcnt vmcnt(0)
	v_lshlrev_b32_e32 v64, 3, v62
	v_bfe_u32 v83, v3, 3, 3
	v_and_b32_e32 v4, 7, v3
	v_writelane_b32 v252, s91, 61
	v_cndmask_b32_e32 v73, v3, v2, vcc
	v_and_b32_e32 v2, 0xf8, v64
	v_lshlrev_b32_e32 v68, 2, v4
	v_lshl_add_u32 v85, v4, 4, s17
	v_lshlrev_b32_e32 v70, 3, v4
	v_mul_u32_u24_e32 v4, 0x420, v4
	v_lshlrev_b32_e32 v5, 2, v83
	s_add_i32 s51, 0, 0x20024
	v_writelane_b32 v252, s66, 62
	v_cndmask_b32_e64 v81, 0, 48, vcc
	s_mov_b64 s[92:93], s[6:7]
	v_mov_b32_e32 v67, 0
	v_mul_u32_u24_e32 v87, 0x84, v83
	v_or_b32_e32 v93, 8, v83
	v_or_b32_e32 v94, 16, v83
	v_or_b32_e32 v95, 24, v83
	v_add3_u32 v96, s17, v4, v5
	v_lshl_add_u32 v97, v62, 2, s17
	v_add_u32_e32 v72, 0x1ef, v62
	v_lshlrev_b32_e32 v98, 2, v73
	v_lshl_add_u32 v99, v73, 1, v73
	v_lshlrev_b32_e32 v100, 1, v73
	v_mov_b32_e32 v101, 8
	v_mov_b32_e32 v102, 1
	v_mov_b32_e32 v103, 3
	v_lshlrev_b32_e32 v74, 2, v2
	v_mov_b32_e32 v104, 0x204
	v_mov_b32_e32 v105, 0x3000
	v_mov_b32_e32 v106, 0x6000
	v_mov_b32_e32 v107, 0x9000
	v_mov_b32_e32 v108, 0xc000
	v_mov_b32_e32 v109, 0xf000
	v_mov_b32_e32 v110, 0x12000
	v_mov_b32_e32 v111, 0x15000
	v_mbcnt_hi_u32_b32 v112, -1, v63
	s_add_i32 s21, 0, 0x20048
	s_add_i32 s33, 0, 0x20044
	s_add_i32 s72, 0, 0x20040
	s_movk_i32 s18, 0x53ff
	s_add_i32 s77, 0, 0x20020
	s_movk_i32 s19, 0x7fff
	s_mov_b32 s8, 0xffff0000
	s_mov_b32 s12, 0
	v_cmp_eq_u32_e64 s[38:39], 0, v3
	v_cmp_eq_u32_e64 s[42:43], 0, v62
	s_mov_b64 s[10:11], 0x1000
	v_writelane_b32 v252, s67, 63
	v_writelane_b32 v253, s51, 0
	s_barrier
	s_branch .LBB0_19

.LBB0_65:
	s_or_b64 exec, exec, s[6:7]
	s_mov_b64 s[6:7], exec
	v_mbcnt_lo_u32_b32 v2, s6, 0
	v_mbcnt_hi_u32_b32 v2, s7, v2
	v_cmp_eq_u32_e32 vcc, 0, v2
	s_waitcnt vmcnt(0)
	buffer_inv sc1
	s_and_saveexec_b64 s[28:29], vcc
	s_cbranch_execz .LBB0_67
	s_bcnt1_i32_b64 s2, s[6:7]
	v_mov_b32_e32 v2, s2
.LBB0_67:
	s_or_b64 exec, exec, s[28:29]
	s_waitcnt vmcnt(0)
	v_mov_b32_e32 v3, 0

.LBB0_274:
	v_readlane_b32 s0, v252, 0
	v_readlane_b32 s1, v252, 1
	s_load_dwordx4 s[4:7], s[0:1], 0x70
	s_add_u32 s0, s90, 0x10000
	s_movk_i32 s82, 0xa0
	s_mov_b32 s62, -1
	s_mov_b32 s63, 0x20000
	s_waitcnt lgkmcnt(0)
	v_writelane_b32 v253, s4, 2
	v_mov_b32_e32 v147, 0
	v_mov_b32_e32 v209, 0x358637bd
	v_writelane_b32 v253, s5, 3
	v_writelane_b32 v253, s6, 4
	v_writelane_b32 v253, s7, 5
	v_writelane_b32 v253, s0, 10
	s_addc_u32 s0, s91, 0
	s_ashr_i32 s96, s3, 31
	s_ashr_i32 s83, s97, 31
	v_writelane_b32 v253, s0, 11
	s_add_u32 s0, s90, 0x4200
	s_addc_u32 s1, s91, 0
	s_add_u32 s52, s90, 0x4400
	s_addc_u32 s53, s91, 0
	s_add_u32 s68, s90, 0x4500
	v_writelane_b32 v252, s0, 28
	s_addc_u32 s69, s91, 0
	v_mov_b32_e32 v210, 0xbf1f24be
	v_writelane_b32 v252, s1, 29
	s_add_u32 s0, s90, 0x4600
	s_addc_u32 s1, s91, 0
	v_writelane_b32 v252, s0, 56
	v_mov_b32_e32 v211, 0x3e642e9d
	v_mov_b32_e32 v212, 8
	v_writelane_b32 v252, s1, 57
	s_add_u32 s0, s90, 0x4700
	s_addc_u32 s1, s91, 0
	v_writelane_b32 v252, s0, 62
	v_mov_b32_e32 v213, 3
	v_mov_b32_e32 v214, 0x204
	v_writelane_b32 v252, s1, 63
	s_add_u32 s0, s90, 0x4800
	s_addc_u32 s1, s91, 0
	v_writelane_b32 v253, s0, 0
	v_mov_b32_e32 v215, 0x3000
	v_mov_b32_e32 v216, 0x6000
	v_writelane_b32 v253, s1, 1
	s_add_u32 s0, s90, 0x4900
	s_addc_u32 s1, s91, 0
	v_writelane_b32 v252, s0, 52
	v_mov_b32_e32 v217, 0x9000
	v_mov_b32_e32 v218, 0xc000
	v_writelane_b32 v252, s1, 53
	s_add_u32 s0, s90, 0x4a00
	s_addc_u32 s1, s91, 0
	s_add_u32 s74, s90, 0x4b00
	v_writelane_b32 v253, s0, 6
	s_addc_u32 s75, s91, 0
	v_mov_b32_e32 v219, 0xf000
	v_writelane_b32 v253, s1, 7
	s_add_u32 s0, s90, 0x4c00
	s_addc_u32 s1, s91, 0
	s_add_u32 s4, s90, 0x4d00
	s_addc_u32 s5, s91, 0
	s_add_u32 s6, s90, 0x4e00
	s_addc_u32 s7, s91, 0
	s_add_u32 s54, s90, 0x4f00
	s_addc_u32 s55, s91, 0
	s_add_u32 s80, s90, 0x5000
	s_addc_u32 s81, s91, 0
	s_add_u32 s56, s90, 0x5100
	s_addc_u32 s57, s91, 0
	s_add_u32 s58, s90, 0x5200
	s_addc_u32 s59, s91, 0
	s_add_u32 s78, s90, 0x5300
	s_addc_u32 s79, s91, 0
	s_cmp_eq_u32 s13, 15
	s_cselect_b64 s[8:9], -1, 0
	v_writelane_b32 v253, s8, 12
	s_cmp_eq_u32 s13, 14
	v_mov_b32_e32 v220, 0x12000
	v_writelane_b32 v253, s9, 13
	s_cselect_b64 s[8:9], -1, 0
	v_writelane_b32 v253, s8, 14
	s_cmp_eq_u32 s13, 13
	v_mov_b32_e32 v221, 0x15000
	v_writelane_b32 v253, s9, 15
	s_cselect_b64 s[8:9], -1, 0
	v_writelane_b32 v253, s8, 16
	s_cmp_eq_u32 s13, 12
	v_mbcnt_hi_u32_b32 v222, -1, v63
	v_writelane_b32 v253, s9, 17
	s_cselect_b64 s[8:9], -1, 0
	v_writelane_b32 v253, s8, 18
	s_cmp_eq_u32 s13, 11
	v_mov_b32_e32 v223, 0x7fc00000
	v_writelane_b32 v253, s9, 19
	s_cselect_b64 s[8:9], -1, 0
	v_writelane_b32 v253, s8, 20
	s_cmp_eq_u32 s13, 10
	v_mov_b64_e32 v[150:151], 0x500
	v_writelane_b32 v253, s9, 21
	s_cselect_b64 s[8:9], -1, 0
	v_writelane_b32 v253, s8, 22
	s_cmp_eq_u32 s13, 9
	v_mov_b64_e32 v[152:153], 0x4ff
	v_writelane_b32 v253, s9, 23
	s_cselect_b64 s[8:9], -1, 0
	v_writelane_b32 v253, s8, 24
	s_cmp_eq_u32 s13, 8
	v_mov_b64_e32 v[226:227], 0xf00
	v_writelane_b32 v253, s9, 25
	s_cselect_b64 s[8:9], -1, 0
	v_writelane_b32 v253, s8, 26
	s_cmp_eq_u32 s13, 7
	v_mov_b64_e32 v[148:149], 0xeff
	v_writelane_b32 v253, s9, 27
	s_cselect_b64 s[8:9], -1, 0
	v_writelane_b32 v253, s8, 28
	s_cmp_eq_u32 s13, 6
	v_mov_b64_e32 v[158:159], 0x280
	v_writelane_b32 v253, s9, 29
	s_cselect_b64 s[8:9], -1, 0
	v_writelane_b32 v253, s8, 30
	s_cmp_eq_u32 s13, 5
	v_mov_b64_e32 v[160:161], 0x27f
	v_writelane_b32 v253, s9, 31
	s_cselect_b64 s[8:9], -1, 0
	v_writelane_b32 v253, s8, 32
	s_cmp_eq_u32 s13, 4
	v_mov_b32_e32 v224, 0x2000
	v_writelane_b32 v253, s9, 33
	s_cselect_b64 s[8:9], -1, 0
	v_writelane_b32 v253, s8, 34
	s_cmp_eq_u32 s13, 3
	v_mov_b32_e32 v225, 0x800
	v_writelane_b32 v253, s9, 35
	s_cselect_b64 s[8:9], -1, 0
	v_writelane_b32 v253, s8, 36
	s_cmp_eq_u32 s13, 2
	v_mov_b64_e32 v[162:163], 0xc0
	v_writelane_b32 v253, s9, 37
	s_cselect_b64 s[8:9], -1, 0
	v_writelane_b32 v253, s8, 38
	s_cmp_eq_u32 s13, 1
	v_mov_b64_e32 v[164:165], 0xbf
	v_writelane_b32 v253, s9, 39
	s_cselect_b64 s[8:9], -1, 0
	v_writelane_b32 v253, s8, 40
	s_cmp_eq_u32 s13, 0
	v_mov_b64_e32 v[166:167], 0x80
	v_writelane_b32 v253, s9, 41
	s_cselect_b64 s[8:9], -1, 0
	v_writelane_b32 v253, s8, 42
	v_mov_b64_e32 v[168:169], 0x7f
	s_mov_b32 s51, 0x33300000
	v_writelane_b32 v253, s9, 43
	s_lshl_b64 s[8:9], s[16:17], 2
	s_add_u32 s2, s48, s8
	s_addc_u32 s8, s49, s9
	s_add_u32 s10, s2, 0x1400
	s_addc_u32 s11, s8, 0
	v_writelane_b32 v253, s10, 44
	s_movk_i32 s76, 0x7fff
	s_mov_b32 s77, 0xffff0000
	v_writelane_b32 v253, s11, 45
	s_add_u32 s10, s90, 0x7400
	s_addc_u32 s11, s91, 0
	v_writelane_b32 v253, s10, 46
	s_mov_b32 s50, 0x3b3504f3
	s_nop 0
	v_writelane_b32 v253, s11, 47
	s_add_u32 s10, s90, 0x7500
	s_addc_u32 s11, s91, 0
	v_writelane_b32 v252, s10, 32
	s_nop 1
	v_writelane_b32 v252, s11, 33
	s_add_u32 s10, s90, 0x7500
	s_addc_u32 s11, s91, 0
	s_cmpk_lt_i32 s97, 0x500
	s_cselect_b64 s[8:9], -1, 0
	s_lshr_b32 s2, s83, 29
	v_writelane_b32 v253, s8, 48
	s_add_i32 s2, s97, s2
	s_ashr_i32 s21, s2, 3
	v_writelane_b32 v253, s9, 49
	s_and_b32 s8, s2, -8
	s_sub_i32 s20, s97, s8
	s_cmp_gt_i32 s20, -1
	v_writelane_b32 v252, s10, 34
	s_cselect_b64 s[8:9], -1, 0
	s_nop 0
	v_writelane_b32 v252, s11, 35
	s_and_b64 s[10:11], s[8:9], exec
	s_cselect_b32 s2, s82, 0xa1
	s_cmp_lg_u64 s[8:9], 0
	s_mul_i32 s2, s20, s2
	s_subb_u32 s8, 0, s21
	s_add_i32 s11, s8, s2
	s_cmpk_lt_i32 s97, 0xf00
	s_cselect_b64 s[8:9], -1, 0
	s_lshr_b32 s2, s3, 31
	v_writelane_b32 v253, s8, 50
	s_add_i32 s2, s3, s2
	s_ashr_i32 s10, s2, 1
	v_writelane_b32 v253, s9, 51
	s_ashr_i32 s2, s12, 5
	v_writelane_b32 v253, s2, 52
	s_mulk_i32 s2, 0x280
	s_addk_i32 s2, 0x27f
	v_writelane_b32 v253, s2, 53
	s_lshl_b32 s2, s12, 1
	v_writelane_b32 v253, s2, 54
	s_and_b32 s2, s2, 62
	s_add_i32 s10, s10, s97
	v_writelane_b32 v253, s2, 55
	s_lshl_b32 s2, s3, 1
	s_cmp_gt_i32 s97, -1
	s_cselect_b64 s[12:13], -1, 0
	s_cmpk_eq_i32 s3, 0x100
	s_cselect_b64 s[30:31], -1, 0
	s_and_b64 s[8:9], s[30:31], exec
	s_cselect_b32 s25, 48, s3
	v_writelane_b32 v253, s2, 56
	s_cselect_b32 s2, 0xffffffd0, 0
	s_cselect_b32 s14, 48, 0
	s_cselect_b32 s26, 32, s3
	s_cselect_b32 s22, 0xffffffb0, 0
	s_cselect_b32 s23, 0x50, 0
	s_cselect_b32 s27, 0xb0, s3
	s_cselect_b32 s24, 0x50, s3
	s_cmp_lt_i32 s97, s25
	s_cselect_b64 s[8:9], -1, 0
	s_and_b64 s[8:9], s[12:13], s[8:9]
	v_writelane_b32 v253, s8, 57
	s_nop 1
	v_writelane_b32 v253, s9, 58
	s_ashr_i32 s8, s25, 31
	s_cmp_ge_i32 s97, s14
	v_writelane_b32 v253, s8, 59
	s_cselect_b64 s[8:9], -1, 0
	s_cmp_lt_i32 s97, s24
	s_cselect_b64 s[14:15], -1, 0
	s_and_b64 s[8:9], s[8:9], s[14:15]
	v_writelane_b32 v253, s8, 60
	s_nop 1
	v_writelane_b32 v253, s9, 61
	s_add_i32 s9, s2, s97
	s_ashr_i32 s2, s26, 31
	s_cmp_ge_i32 s97, s23
	s_cselect_b64 s[16:17], -1, 0
	s_cmp_lt_i32 s97, s3
	s_cselect_b64 s[18:19], -1, 0
	v_writelane_b32 v253, s2, 62
	s_and_b64 s[16:17], s[18:19], s[16:17]
	v_writelane_b32 v253, s16, 63
	s_and_b64 s[12:13], s[12:13], s[14:15]
	s_lshl_b32 s2, s24, 3
	v_writelane_b32 v254, s17, 0
	v_writelane_b32 v254, s12, 1
	s_add_i32 s8, s22, s97
	s_and_b32 s18, s97, 15
	v_writelane_b32 v254, s13, 2
	s_sub_i32 s12, s97, s23
	s_ashr_i32 s13, s27, 31
	v_writelane_b32 v254, s2, 3
	s_add_i32 s2, s23, s97
	v_writelane_b32 v252, s13, 50
	s_lshl_b32 s13, s97, 3
	s_ashr_i32 s22, s12, 4
	s_ashr_i32 s24, s27, 4
	s_cmp_gt_i32 s12, -1
	v_writelane_b32 v254, s13, 4
	s_cselect_b64 s[14:15], -1, 0
	s_and_b32 s13, s27, -16
	s_cmp_lt_i32 s12, s13
	s_cselect_b64 s[12:13], -1, 0
	s_cmp_gt_u32 s27, 15
	s_cselect_b64 s[16:17], -1, 0
	s_and_b64 s[16:17], s[16:17], s[12:13]
	s_lshl_b32 s12, s18, 7
	s_cmpk_lt_i32 s22, 0x140
	v_writelane_b32 v254, s12, 5
	s_cselect_b64 s[12:13], -1, 0
	v_writelane_b32 v254, s12, 6
	s_addk_i32 s11, 0xa0
	s_nop 0
	v_writelane_b32 v254, s13, 7
	s_ashr_i32 s12, s11, 31
	s_lshr_b32 s12, s12, 27
	s_add_i32 s12, s11, s12
	s_and_b32 s13, s12, 0xffffffe0
	s_ashr_i32 s12, s12, 5
	s_sub_i32 s11, s11, s13
	s_lshl_b32 s13, s18, 6
	s_lshl_b32 s12, s12, 2
	v_writelane_b32 v254, s13, 8
	s_sub_i32 s13, 0xa0, s12
	s_min_i32 s13, s13, 4
	s_cmp_lt_i32 s20, 0
	s_movk_i32 s18, 0x1e1
	s_cselect_b32 s18, s18, 0x1e0
	s_cselect_b32 s19, 0xa1, s82
	s_and_b64 s[14:15], s[14:15], s[16:17]
	v_writelane_b32 v254, s14, 9
	s_nop 1
	v_writelane_b32 v254, s15, 10
	s_mul_i32 s14, s20, s18
	s_add_i32 s14, s14, s21
	s_mul_hi_i32 s15, s14, 0x2aaaaaab
	s_lshr_b32 s16, s15, 31
	s_ashr_i32 s15, s15, 4
	s_add_i32 s15, s15, s16
	s_mul_i32 s16, s15, 0x60
	s_sub_i32 s14, s14, s16
	s_bfe_i32 s16, s14, 0x80000
	s_bfe_u32 s16, s16, 0x2000d
	s_add_i32 s16, s14, s16
	s_and_b32 s17, s16, 0xfc
	s_sub_i32 s14, s14, s17
	s_lshl_b32 s15, s15, 2
	s_sext_i32_i8 s14, s14
	s_add_i32 s23, s15, s14
	s_mul_i32 s14, s20, s19
	s_add_i32 s14, s14, s21
	s_mul_hi_i32 s15, s14, 0x66666667
	s_lshr_b32 s17, s15, 31
	s_ashr_i32 s15, s15, 8
	s_add_i32 s15, s15, s17
	s_mul_i32 s17, s15, 0x280
	s_sub_i32 s17, s14, s17
	s_bfe_u32 s18, s17, 0x2001d
	s_add_i32 s18, s17, s18
	s_and_b32 s19, s18, 0xfffc
	s_sub_i32 s17, s17, s19
	s_lshl_b32 s15, s15, 2
	s_sext_i32_i16 s17, s17
	s_add_i32 s20, s15, s17
	s_ashr_i32 s15, s14, 31
	s_lshr_b32 s15, s15, 27
	s_add_i32 s15, s14, s15
	s_and_b32 s17, s15, 0xffe0
	s_sub_i32 s14, s14, s17
	s_bfe_i32 s17, s14, 0x80000
	s_bfe_u32 s17, s17, 0x2000d
	s_add_i32 s17, s14, s17
	s_and_b32 s19, s17, 0xfc
	s_sub_i32 s14, s14, s19
	s_ashr_i32 s15, s15, 5
	s_lshl_b32 s15, s15, 2
	s_sext_i32_i8 s14, s14
	s_add_i32 s21, s15, s14
	s_abs_i32 s14, s3
	v_cvt_f32_u32_e32 v1, s14
	s_sub_i32 s15, 0, s14
	s_bfe_i32 s16, s16, 0x80000
	s_sext_i32_i16 s16, s16
	v_rcp_iflag_f32_e32 v1, v1
	s_nop 0
	v_mul_f32_e32 v1, 0x4f7ffffe, v1
	v_cvt_u32_f32_e32 v1, v1
	s_nop 0
	v_readfirstlane_b32 s19, v1
	s_mul_i32 s15, s15, s19
	s_mul_hi_u32 s15, s19, s15
	s_add_i32 s15, s19, s15
	s_ashr_i32 s19, s16, 2
	v_writelane_b32 v254, s19, 11
	s_lshl_b32 s19, s19, 20
	s_or_b32 s29, s19, 0x80000
	v_writelane_b32 v254, s29, 12
	v_writelane_b32 v254, s23, 13
	s_lshl_b32 s23, s23, 20
	s_or_b32 s29, s23, 0x80000
	v_writelane_b32 v254, s29, 14
	s_or_b32 s29, s19, 0x80
	v_writelane_b32 v254, s29, 15
	v_writelane_b32 v254, s23, 16
	s_bitset1_b32 s23, 7
	v_writelane_b32 v254, s23, 17
	s_sext_i32_i16 s16, s18
	v_writelane_b32 v254, s19, 18
	s_or_b32 s19, s19, 0x80080
	s_ashr_i32 s18, s16, 2
	v_writelane_b32 v254, s19, 19
	v_writelane_b32 v254, s18, 20
	s_lshl_b32 s18, s18, 20
	s_or_b32 s19, s18, 0x80000
	v_writelane_b32 v254, s19, 21
	s_lshl_b32 s19, s20, 20
	v_writelane_b32 v254, s20, 22
	s_or_b32 s20, s19, 0x80000
	v_writelane_b32 v254, s20, 23
	s_or_b32 s20, s18, 0x80
	v_writelane_b32 v254, s20, 24
	s_bfe_i32 s16, s17, 0x80000
	v_writelane_b32 v254, s19, 25
	s_bitset1_b32 s19, 7
	s_sext_i32_i16 s16, s16
	v_writelane_b32 v254, s19, 26
	s_ashr_i32 s28, s16, 2
	v_writelane_b32 v254, s18, 27
	s_or_b32 s18, s18, 0x80080
	v_writelane_b32 v254, s18, 28
	s_lshl_b32 s18, s28, 20
	s_or_b32 s19, s18, 0x80000
	v_writelane_b32 v254, s19, 29
	s_lshl_b32 s19, s21, 20
	s_or_b32 s20, s19, 0x80000
	v_writelane_b32 v254, s20, 30
	s_or_b32 s20, s18, 0x80
	v_writelane_b32 v254, s20, 31
	v_writelane_b32 v254, s19, 32
	s_bitset1_b32 s19, 7
	v_writelane_b32 v254, s19, 33
	v_writelane_b32 v254, s18, 34
	s_or_b32 s18, s18, 0x80080
	v_writelane_b32 v254, s18, 35
	s_mul_i32 s18, s28, 0x2c0000
	v_writelane_b32 v254, s28, 36
	s_add_i32 s19, s18, 0x160000
	v_writelane_b32 v254, s19, 37
	s_mul_i32 s19, s21, 0x2c0000
	v_writelane_b32 v254, s21, 38
	s_or_b32 s20, s19, 0x4000
	v_writelane_b32 v254, s20, 39
	s_or_b32 s20, s18, 0x80
	v_writelane_b32 v254, s20, 40
	s_mul_hi_u32 s16, s15, 0x1b80
	v_writelane_b32 v254, s19, 41
	s_bitset1_b32 s19, 15
	s_mul_i32 s17, s16, s14
	v_writelane_b32 v254, s19, 42
	s_sub_i32 s17, 0x1b80, s17
	v_writelane_b32 v254, s18, 43
	s_add_i32 s18, s18, 0x160080
	v_writelane_b32 v254, s18, 44
	s_add_i32 s18, s16, 1
	s_sub_i32 s19, s17, s14
	s_cmp_ge_u32 s17, s14
	s_cselect_b32 s16, s18, s16
	s_cselect_b32 s17, s19, s17
	s_add_i32 s18, s16, 1
	s_cmp_ge_u32 s17, s14
	s_cselect_b32 s16, s18, s16
	s_xor_b32 s16, s16, s96
	s_sub_i32 s28, s16, s96
	s_cmp_eq_u32 s28, 1
	v_readlane_b32 s18, v252, 10
	s_cselect_b64 s[16:17], -1, 0
	v_readlane_b32 s19, v252, 11
	s_and_b64 s[16:17], s[18:19], s[16:17]
	v_writelane_b32 v254, s16, 45
	s_cmp_lt_i32 s28, 1
	s_nop 0
	v_writelane_b32 v254, s17, 46
	s_cselect_b64 s[16:17], -1, 0
	v_writelane_b32 v254, s16, 47
	s_cmp_gt_i32 s28, -1
	s_nop 0
	v_writelane_b32 v254, s17, 48
	s_cselect_b64 s[16:17], -1, 0
	v_writelane_b32 v254, s16, 49
	s_add_i32 s20, s28, -2
	v_writelane_b32 v252, s20, 60
	v_writelane_b32 v254, s17, 50
	s_abs_i32 s16, s13
	v_cvt_f32_u32_e32 v1, s16
	s_sub_i32 s17, 0, s16
	v_writelane_b32 v252, s27, 48
	v_writelane_b32 v252, s28, 20
	v_rcp_iflag_f32_e32 v1, v1
	s_nop 0
	v_mul_f32_e32 v1, 0x4f7ffffe, v1
	v_cvt_u32_f32_e32 v1, v1
	s_nop 0
	v_readfirstlane_b32 s18, v1
	s_mul_i32 s17, s17, s18
	s_mul_hi_u32 s17, s18, s17
	s_add_i32 s18, s18, s17
	s_abs_i32 s17, s11
	s_mul_hi_u32 s18, s17, s18
	s_mul_i32 s19, s18, s16
	s_sub_i32 s17, s17, s19
	s_xor_b32 s19, s11, s13
	s_ashr_i32 s19, s19, 31
	s_add_i32 s20, s18, 1
	s_sub_i32 s21, s17, s16
	s_cmp_ge_u32 s17, s16
	s_cselect_b32 s18, s20, s18
	s_cselect_b32 s17, s21, s17
	s_add_i32 s20, s18, 1
	s_cmp_ge_u32 s17, s16
	s_cselect_b32 s16, s20, s18
	s_xor_b32 s16, s16, s19
	s_sub_i32 s16, s16, s19
	s_mul_i32 s13, s16, s13
	s_sub_i32 s11, s11, s13
	s_add_i32 s17, s12, s11
	s_abs_i32 s11, s10
	s_mul_hi_u32 s12, s11, s15
	s_mul_i32 s12, s12, s14
	s_sub_i32 s11, s11, s12
	s_mul_i32 s12, s16, 0x2c0000
	s_add_i32 s13, s12, 0x160000
	v_writelane_b32 v254, s13, 51
	s_mul_i32 s13, s17, 0x2c0000
	s_or_b32 s15, s13, 0x4000
	v_writelane_b32 v254, s15, 52
	s_or_b32 s15, s12, 0x80
	v_writelane_b32 v254, s15, 53
	v_writelane_b32 v254, s13, 54
	s_bitset1_b32 s13, 15
	v_writelane_b32 v254, s13, 55
	v_writelane_b32 v254, s12, 56
	s_add_i32 s12, s12, 0x160080
	s_ashr_i32 s10, s10, 31
	v_writelane_b32 v254, s12, 57
	s_sub_i32 s12, s11, s14
	s_cmp_ge_u32 s11, s14
	s_cselect_b32 s11, s12, s11
	s_sub_i32 s12, s11, s14
	s_cmp_ge_u32 s11, s14
	s_cselect_b32 s11, s12, s11
	s_xor_b32 s11, s11, s10
	s_sub_i32 s12, s11, s10
	s_cmpk_lt_i32 s12, 0x280
	s_cselect_b64 s[10:11], -1, 0
	v_writelane_b32 v254, s10, 58
	s_mov_b32 s20, 0x3ab504f3
	s_nop 0
	v_writelane_b32 v254, s11, 59
	s_ashr_i32 s10, s12, 31
	v_writelane_b32 v254, s10, 60
	s_lshr_b32 s10, s10, 29
	s_add_i32 s10, s12, s10
	s_ashr_i32 s11, s10, 3
	s_and_b32 s10, s10, -8
	s_sub_i32 s10, s12, s10
	v_writelane_b32 v254, s12, 61
	s_cmp_lt_i32 s10, 0
	s_movk_i32 s12, 0x51
	s_cselect_b32 s12, s12, 0x50
	s_mul_i32 s10, s10, s12
	s_add_i32 s10, s10, s11
	s_ashr_i32 s11, s10, 31
	s_lshr_b32 s11, s11, 28
	s_add_i32 s11, s10, s11
	s_and_b32 s12, s11, 0xfff0
	s_sub_i32 s10, s10, s12
	s_bfe_i32 s12, s10, 0x80000
	s_bfe_u32 s12, s12, 0x2000d
	s_add_i32 s12, s10, s12
	s_and_b32 s13, s12, 0xfc
	s_sub_i32 s10, s10, s13
	s_ashr_i32 s11, s11, 4
	s_lshl_b32 s11, s11, 2
	s_sext_i32_i8 s10, s10
	s_add_i32 s14, s11, s10
	s_abs_i32 s10, s25
	v_cvt_f32_u32_e32 v1, s10
	s_sub_i32 s11, 0, s10
	s_bfe_i32 s12, s12, 0x80000
	s_sext_i32_i16 s12, s12
	v_rcp_iflag_f32_e32 v1, v1
	v_writelane_b32 v254, s25, 62
	s_ashr_i32 s12, s12, 2
	v_writelane_b32 v254, s12, 63
	v_mul_f32_e32 v1, 0x4f7ffffe, v1
	v_cvt_u32_f32_e32 v1, v1
	s_lshl_b32 s12, s12, 20
	v_readfirstlane_b32 s13, v1
	s_mul_i32 s11, s11, s13
	s_mul_hi_u32 s11, s13, s11
	s_add_i32 s13, s13, s11
	s_abs_i32 s11, s97
	s_mul_hi_u32 s13, s11, s13
	s_mul_i32 s13, s13, s10
	s_sub_i32 s11, s11, s13
	s_or_b32 s13, s12, 0x80000
	v_writelane_b32 v255, s13, 0
	s_lshl_b32 s13, s14, 20
	v_writelane_b32 v255, s14, 1
	s_or_b32 s14, s13, 0x80000
	v_writelane_b32 v255, s14, 2
	s_or_b32 s14, s12, 0x80
	v_writelane_b32 v255, s14, 3
	v_writelane_b32 v255, s13, 4
	s_bitset1_b32 s13, 7
	v_writelane_b32 v255, s13, 5
	v_writelane_b32 v255, s12, 6
	s_or_b32 s12, s12, 0x80080
	v_writelane_b32 v255, s12, 7
	s_sub_i32 s12, s11, s10
	s_cmp_ge_u32 s11, s10
	s_cselect_b32 s11, s12, s11
	s_sub_i32 s12, s11, s10
	s_cmp_ge_u32 s11, s10
	s_cselect_b32 s10, s12, s11
	s_abs_i32 s11, s26
	v_cvt_f32_u32_e32 v1, s11
	s_sub_i32 s12, 0, s11
	s_xor_b32 s10, s10, s83
	v_writelane_b32 v255, s26, 8
	v_rcp_iflag_f32_e32 v1, v1
	s_sub_i32 s10, s10, s83
	v_writelane_b32 v255, s10, 9
	v_mul_f32_e32 v1, 0x4f7ffffe, v1
	v_cvt_u32_f32_e32 v1, v1
	s_nop 0
	v_readfirstlane_b32 s13, v1
	s_mul_i32 s12, s12, s13
	s_mul_hi_u32 s12, s13, s12
	s_add_i32 s13, s13, s12
	s_abs_i32 s12, s9
	s_mul_hi_u32 s13, s12, s13
	s_mul_i32 s13, s13, s11
	s_sub_i32 s12, s12, s13
	s_ashr_i32 s9, s9, 31
	s_sub_i32 s10, s12, s11
	s_cmp_ge_u32 s12, s11
	s_cselect_b32 s10, s10, s12
	s_sub_i32 s12, s10, s11
	s_cmp_ge_u32 s10, s11
	s_cselect_b32 s10, s12, s10
	s_xor_b32 s10, s10, s9
	s_sub_i32 s9, s10, s9
	v_writelane_b32 v255, s9, 10
	s_abs_i32 s9, s27
	v_cvt_f32_u32_e32 v1, s9
	s_sub_i32 s10, 0, s9
	v_rcp_iflag_f32_e32 v1, v1
	s_nop 0
	v_mul_f32_e32 v1, 0x4f7ffffe, v1
	v_cvt_u32_f32_e32 v1, v1
	s_nop 0
	v_readfirstlane_b32 s11, v1
	s_mul_i32 s10, s10, s11
	s_mul_hi_u32 s10, s11, s10
	s_add_i32 s11, s11, s10
	s_abs_i32 s10, s8
	s_mul_hi_u32 s12, s10, s11
	s_mul_i32 s12, s12, s9
	s_sub_i32 s10, s10, s12
	s_ashr_i32 s8, s8, 31
	s_sub_i32 s12, s10, s9
	s_cmp_ge_u32 s10, s9
	s_cselect_b32 s10, s12, s10
	s_sub_i32 s12, s10, s9
	s_cmp_ge_u32 s10, s9
	s_cselect_b32 s10, s12, s10
	s_xor_b32 s10, s10, s8
	s_sub_i32 s8, s10, s8
	v_writelane_b32 v255, s8, 11
	s_abs_i32 s8, s2
	s_mul_hi_u32 s10, s8, s11
	s_mul_i32 s10, s10, s9
	s_sub_i32 s8, s8, s10
	s_ashr_i32 s2, s2, 31
	s_sub_i32 s10, s8, s9
	s_cmp_ge_u32 s8, s9
	s_cselect_b32 s8, s10, s8
	s_sub_i32 s10, s8, s9
	s_cmp_ge_u32 s8, s9
	s_cselect_b32 s8, s10, s8
	s_xor_b32 s8, s8, s2
	s_sub_i32 s2, s8, s2
	v_writelane_b32 v255, s2, 12
	s_mul_hi_i32 s2, s28, s3
	v_writelane_b32 v255, s2, 13
	s_mul_i32 s2, s28, s3
	v_writelane_b32 v255, s2, 14
	s_lshl_b32 s2, s16, 20
	v_writelane_b32 v255, s16, 15
	s_or_b32 s8, s2, 0x80000
	v_writelane_b32 v255, s8, 16
	s_lshl_b32 s8, s17, 20
	v_writelane_b32 v255, s17, 17
	s_or_b32 s9, s8, 0x80000
	v_writelane_b32 v255, s9, 18
	s_or_b32 s9, s2, 0x80
	v_writelane_b32 v255, s9, 19
	v_writelane_b32 v255, s8, 20
	s_bitset1_b32 s8, 7
	v_writelane_b32 v255, s8, 21
	s_ashr_i32 s23, s22, 31
	v_writelane_b32 v255, s2, 22
	s_or_b32 s2, s2, 0x80080
	v_writelane_b32 v255, s2, 23
	s_lshl_b64 s[12:13], s[22:23], 19
	s_ashr_i32 s25, s24, 31
	v_writelane_b32 v255, s12, 24
	s_add_i32 s2, 0, 0x20060
	v_writelane_b32 v253, s2, 8
	v_writelane_b32 v255, s13, 25
	s_lshl_b64 s[12:13], s[24:25], 19
	v_writelane_b32 v255, s12, 26
	s_add_i32 s2, 0, 0x20048
	v_writelane_b32 v252, s2, 26
	v_writelane_b32 v255, s13, 27
	s_lshl_b64 s[12:13], s[22:23], 18
	v_writelane_b32 v255, s12, 28
	s_add_i32 s2, 0, 0x20044
	v_writelane_b32 v252, s2, 22
	v_writelane_b32 v255, s13, 29
	s_lshl_b64 s[12:13], s[24:25], 18
	s_add_i32 s2, 0, 0x20040
	v_writelane_b32 v255, s12, 30
	v_writelane_b32 v252, s2, 24
	s_add_i32 s2, 0, 0x20020
	v_writelane_b32 v255, s13, 31
	s_lshl_b64 s[12:13], s[22:23], 7
	v_writelane_b32 v252, s2, 40
	s_add_i32 s2, 0, 0x20024
	v_writelane_b32 v255, s12, 32
	v_writelane_b32 v252, s2, 42
	s_mov_b32 s2, s22
	v_writelane_b32 v255, s13, 33
	v_writelane_b32 v255, s2, 34
	s_lshl_b64 s[12:13], s[22:23], 8
	v_writelane_b32 v252, s96, 46
	v_writelane_b32 v255, s3, 35
	v_writelane_b32 v255, s12, 36
	v_writelane_b32 v252, s83, 30
	v_writelane_b32 v252, s52, 36
	v_writelane_b32 v255, s13, 37
	s_lshl_b64 s[12:13], s[24:25], 8
	v_writelane_b32 v255, s12, 38
	v_writelane_b32 v252, s53, 37
	v_writelane_b32 v252, s68, 38
	v_writelane_b32 v255, s13, 39
	v_writelane_b32 v255, s30, 40
	v_mov_b32_e32 v1, 1
	s_movk_i32 s10, 0x1000
	v_writelane_b32 v255, s31, 41
	v_writelane_b32 v255, s24, 42
	s_mov_b32 s11, 0x49800000
	s_mov_b32 s8, 0
	s_mov_b32 s17, 0
	s_mov_b64 s[28:29], 0x1000
	v_writelane_b32 v252, s69, 39
	v_writelane_b32 v255, s25, 43
	s_branch .LBB0_279

.LBB0_360:
	s_or_b64 exec, exec, s[30:31]
	s_mov_b64 s[30:31], exec
	v_mbcnt_lo_u32_b32 v2, s30, 0
	v_mbcnt_hi_u32_b32 v2, s31, v2
	v_cmp_eq_u32_e32 vcc, 0, v2
	s_waitcnt vmcnt(0)
	buffer_inv sc1
	s_and_saveexec_b64 s[36:37], vcc
	s_cbranch_execz .LBB0_362
	s_bcnt1_i32_b64 s2, s[30:31]
	v_readlane_b32 s12, v252, 34
	v_mov_b32_e32 v2, s2
	v_readlane_b32 s13, v252, 35
	s_nop 4
.LBB0_362:
	s_or_b64 exec, exec, s[36:37]
	s_waitcnt vmcnt(0)
	v_mov_b32_e32 v3, 0

.LBB0_638:
	s_or_b64 exec, exec, s[30:31]
	s_mov_b64 s[30:31], exec
	v_mbcnt_lo_u32_b32 v2, s30, 0
	v_mbcnt_hi_u32_b32 v2, s31, v2
	v_cmp_eq_u32_e32 vcc, 0, v2
	s_waitcnt vmcnt(0)
	buffer_inv sc1
	s_and_saveexec_b64 s[36:37], vcc
	s_cbranch_execz .LBB0_640
	s_bcnt1_i32_b64 s2, s[30:31]
	v_readlane_b32 s12, v252, 34
	v_mov_b32_e32 v2, s2
	v_readlane_b32 s13, v252, 35
	s_nop 4
.LBB0_640:
	s_or_b64 exec, exec, s[36:37]
	s_waitcnt vmcnt(0)
	v_mov_b32_e32 v3, 0

.LBB0_961:
	s_or_b64 exec, exec, s[30:31]
	s_mov_b64 s[30:31], exec
	v_mbcnt_lo_u32_b32 v2, s30, 0
	v_mbcnt_hi_u32_b32 v2, s31, v2
	v_cmp_eq_u32_e32 vcc, 0, v2
	s_waitcnt vmcnt(0)
	buffer_inv sc1
	s_and_saveexec_b64 s[36:37], vcc
	s_cbranch_execz .LBB0_963
	s_bcnt1_i32_b64 s2, s[30:31]
	v_readlane_b32 s12, v252, 34
	v_mov_b32_e32 v2, s2
	v_readlane_b32 s13, v252, 35
	s_nop 4
.LBB0_963:
	s_or_b64 exec, exec, s[36:37]
	s_waitcnt vmcnt(0)
	v_mov_b32_e32 v3, 0

.LBB0_1369:
	s_or_b64 exec, exec, s[30:31]
	s_mov_b64 s[30:31], exec
	v_mbcnt_lo_u32_b32 v2, s30, 0
	v_mbcnt_hi_u32_b32 v2, s31, v2
	v_cmp_eq_u32_e32 vcc, 0, v2
	s_waitcnt vmcnt(0)
	buffer_inv sc1
	s_and_saveexec_b64 s[36:37], vcc
	s_cbranch_execz .LBB0_1371
	s_bcnt1_i32_b64 s2, s[30:31]
	v_readlane_b32 s12, v252, 34
	v_mov_b32_e32 v2, s2
	v_readlane_b32 s13, v252, 35
	s_nop 4
.LBB0_1371:
	s_or_b64 exec, exec, s[36:37]
	s_waitcnt vmcnt(0)
	v_mov_b32_e32 v3, 0

.LBB0_1647:
	s_or_b64 exec, exec, s[30:31]
	s_mov_b64 s[30:31], exec
	v_mbcnt_lo_u32_b32 v2, s30, 0
	v_mbcnt_hi_u32_b32 v2, s31, v2
	v_cmp_eq_u32_e32 vcc, 0, v2
	s_waitcnt vmcnt(0)
	buffer_inv sc1
	s_and_saveexec_b64 s[36:37], vcc
	s_cbranch_execz .LBB0_1649
	s_bcnt1_i32_b64 s2, s[30:31]
	v_readlane_b32 s12, v252, 34
	v_mov_b32_e32 v2, s2
	v_readlane_b32 s13, v252, 35
	s_nop 4
.LBB0_1649:
	s_or_b64 exec, exec, s[36:37]
	s_waitcnt vmcnt(0)
	v_mov_b32_e32 v3, 0

.LBB0_1936:
	s_or_b64 exec, exec, s[30:31]
	s_mov_b64 s[30:31], exec
	v_mbcnt_lo_u32_b32 v2, s30, 0
	v_mbcnt_hi_u32_b32 v2, s31, v2
	v_cmp_eq_u32_e32 vcc, 0, v2
	s_waitcnt vmcnt(0)
	buffer_inv sc1
	s_and_saveexec_b64 s[36:37], vcc
	s_cbranch_execz .LBB0_1938
	s_bcnt1_i32_b64 s2, s[30:31]
	v_readlane_b32 s12, v252, 34
	v_mov_b32_e32 v2, s2
	v_readlane_b32 s13, v252, 35
	s_nop 4
.LBB0_1938:
	s_or_b64 exec, exec, s[36:37]
	s_waitcnt vmcnt(0)
	v_mov_b32_e32 v3, 0

.LBB0_2232:
	s_or_b64 exec, exec, s[30:31]
	s_mov_b64 s[30:31], exec
	v_mbcnt_lo_u32_b32 v2, s30, 0
	v_mbcnt_hi_u32_b32 v2, s31, v2
	v_cmp_eq_u32_e32 vcc, 0, v2
	s_waitcnt vmcnt(0)
	buffer_inv sc1
	s_and_saveexec_b64 s[36:37], vcc
	s_cbranch_execz .LBB0_2234
	s_bcnt1_i32_b64 s2, s[30:31]
	v_readlane_b32 s12, v252, 34
	v_mov_b32_e32 v2, s2
	v_readlane_b32 s13, v252, 35
	s_nop 4
.LBB0_2234:
	s_or_b64 exec, exec, s[36:37]
	s_waitcnt vmcnt(0)
	v_mov_b32_e32 v3, 0

.LBB0_2508:
	s_or_b64 exec, exec, s[30:31]
	s_mov_b64 s[30:31], exec
	v_mbcnt_lo_u32_b32 v2, s30, 0
	v_mbcnt_hi_u32_b32 v2, s31, v2
	v_cmp_eq_u32_e32 vcc, 0, v2
	s_waitcnt vmcnt(0)
	buffer_inv sc1
	s_and_saveexec_b64 s[36:37], vcc
	s_cbranch_execz .LBB0_2510
	s_bcnt1_i32_b64 s2, s[30:31]
	v_readlane_b32 s12, v252, 34
	v_mov_b32_e32 v2, s2
	v_readlane_b32 s13, v252, 35
	s_nop 4
.LBB0_2510:
	s_or_b64 exec, exec, s[36:37]
	s_waitcnt vmcnt(0)
	v_mov_b32_e32 v3, 0
